# FFN epilogue first-row blocks: zero-inits before row_shr DPP moves replaced by bound_ctrl zero fill
# baseline (speedup 1.0000x reference)
; #define LAS __attribute__((address_space(3)))
; __device__ __forceinline__ u32x4 pack8(const float (&f)[8]) { u32x4 w; w.x = cvt_pk_bf16(f[0], f[1]); w.y = cvt_pk_bf16(f[2], f[3]); w.z = cvt_pk_bf16(f[4], f[5]); w.w = cvt_pk_bf16(f[6], f[7]); return w; }
; __device__ __forceinline__ float dpp_row_shr1(float x) { return __int_as_float(__builtin_amdgcn_update_dpp(0, __float_as_int(x), 0x111, 0xf, 0xf, false)); }
; __device__ __forceinline__ float dpp_row_shr2(float x) { return __int_as_float(__builtin_amdgcn_update_dpp(0, __float_as_int(x), 0x112, 0xf, 0xf, false)); }
;     __device__ __forceinline__ void operator()(const f32x4 (&acc)[2][2][4][2], const Unit& u, int wr, int wc, int fr, int fq) const {
;     ...
;                 if (m == 0) {
;                     if (B > 0) { const LAS float* p = XG + ((B - 1) * 2) * 128 + chl; const f32x4 r0a = *(const LAS f32x4*)p, r0b = *(const LAS f32x4*)(p + 4), r1a = *(const LAS f32x4*)(p + 128), r1b = *(const LAS f32x4*)(p + 132);
; #pragma unroll
;                         for (int j = 0; j < 4; ++j) { q14[j] = r0a[j]; q14[4 + j] = r0b[j]; q15[j] = r1a[j]; q15[4 + j] = r1b[j]; } }
;                     else {
; #pragma unroll
;                         for (int j = 0; j < 8; ++j) { q14[j] = 0.f; q15[j] = 0.f; } }
;                     float p1a[8], p2a[8];
; #pragma unroll
;                     for (int e = 0; e < 8; ++e) { const float s1 = dpp_row_shr1(g8[e]), s2 = dpp_row_shr2(g8[e]);
;                         p1a[e] = (fr >= 1) ? s1 : q15[e]; p2a[e] = (fr >= 2) ? s2 : ((fr == 1) ? q15[e] : q14[e]); }
; #pragma unroll
;                     for (int e = 0; e < 8; e += 2) { const f32x2 gt = (f32x2){w0[e], w0[e + 1]} * (f32x2){p2a[e], p2a[e + 1]} + (f32x2){w1[e], w1[e + 1]} * (f32x2){p1a[e], p1a[e + 1]} + (f32x2){w2[e], w2[e + 1]} * (f32x2){g8[e], g8[e + 1]} + (f32x2){bb[e], bb[e + 1]};
;                         const f32x2 r = gelu_tanh_mul2(gt, (f32x2){u8[e], u8[e + 1]}); o[e] = r.x; o[e + 1] = r.y; }
;     ...
;                 if (!(B == 0 && m == 0 && fr < 2)) *(u32x4*)(ACT + (size_t)(u.pm * BM + rloc) * FF + chg) = pack8(o);
.LBB0_82:
	s_nop 1
	v_lshl_add_u32 v210, s30, 8, v204
	v_mov_b32_dpp v211, v150 row_shr:1 row_mask:0xf bank_mask:0xf bound_ctrl:0
	v_mov_b32_dpp v213, v150 row_shr:2 row_mask:0xf bank_mask:0xf bound_ctrl:0
	v_mov_b32_dpp v212, v151 row_shr:1 row_mask:0xf bank_mask:0xf bound_ctrl:0
	v_mov_b32_dpp v214, v151 row_shr:2 row_mask:0xf bank_mask:0xf bound_ctrl:0
	v_mov_b32_dpp v215, v152 row_shr:1 row_mask:0xf bank_mask:0xf bound_ctrl:0
	v_mov_b32_dpp v217, v152 row_shr:2 row_mask:0xf bank_mask:0xf bound_ctrl:0
	v_mov_b32_dpp v216, v153 row_shr:1 row_mask:0xf bank_mask:0xf bound_ctrl:0
	v_mov_b32_dpp v218, v153 row_shr:2 row_mask:0xf bank_mask:0xf bound_ctrl:0
	v_mov_b32_dpp v219, v146 row_shr:1 row_mask:0xf bank_mask:0xf bound_ctrl:0
	v_mov_b32_dpp v221, v146 row_shr:2 row_mask:0xf bank_mask:0xf bound_ctrl:0
	v_mov_b32_dpp v220, v147 row_shr:1 row_mask:0xf bank_mask:0xf bound_ctrl:0
	v_mov_b32_dpp v222, v147 row_shr:2 row_mask:0xf bank_mask:0xf bound_ctrl:0
	v_mov_b32_dpp v223, v148 row_shr:1 row_mask:0xf bank_mask:0xf bound_ctrl:0
	v_mov_b32_dpp v225, v148 row_shr:2 row_mask:0xf bank_mask:0xf bound_ctrl:0
	v_mov_b32_dpp v224, v149 row_shr:1 row_mask:0xf bank_mask:0xf bound_ctrl:0
	v_mov_b32_dpp v226, v149 row_shr:2 row_mask:0xf bank_mask:0xf bound_ctrl:0
	s_and_saveexec_b64 s[8:9], s[58:59]
	s_xor_b64 s[30:31], exec, s[8:9]
	s_cbranch_execz .LBB0_84
	s_waitcnt lgkmcnt(0)
	v_cndmask_b32_e64 v170, v170, v174, s[42:43]
	v_cndmask_b32_e64 v171, v171, v175, s[42:43]
	v_cndmask_b32_e64 v164, v164, v168, s[42:43]
	v_cndmask_b32_e64 v165, v165, v169, s[42:43]
	v_cndmask_b32_e64 v162, v162, v166, s[42:43]
	v_cndmask_b32_e64 v163, v163, v167, s[42:43]
	v_cndmask_b32_e64 v170, v170, v221, s[38:39]
	v_cndmask_b32_e64 v171, v171, v222, s[38:39]
	v_cndmask_b32_e64 v164, v164, v217, s[38:39]
	v_cndmask_b32_e64 v165, v165, v218, s[38:39]
	v_cndmask_b32_e64 v162, v162, v213, s[38:39]
	v_cndmask_b32_e64 v163, v163, v214, s[38:39]
	s_waitcnt vmcnt(0)
	v_pk_mul_f32 v[170:171], v[66:67], v[170:171]
	v_cndmask_b32_e64 v174, v219, v174, s[40:41]
	v_cndmask_b32_e64 v175, v220, v175, s[40:41]
	v_pk_mul_f32 v[164:165], v[92:93], v[164:165]
	v_cndmask_b32_e64 v168, v215, v168, s[40:41]
	v_cndmask_b32_e64 v169, v216, v169, s[40:41]
	v_pk_mul_f32 v[162:163], v[90:91], v[162:163]
	v_cndmask_b32_e64 v166, v211, v166, s[40:41]
	v_cndmask_b32_e64 v167, v212, v167, s[40:41]
	v_pk_fma_f32 v[170:171], v[70:71], v[174:175], v[170:171]
	v_pk_fma_f32 v[164:165], v[96:97], v[168:169], v[164:165]
	v_pk_fma_f32 v[162:163], v[94:95], v[166:167], v[162:163]
	v_cndmask_b32_e64 v172, v172, v176, s[42:43]
	v_cndmask_b32_e64 v173, v173, v177, s[42:43]
	v_pk_fma_f32 v[170:171], v[146:147], v[74:75], v[170:171]
	v_pk_fma_f32 v[164:165], v[152:153], v[100:101], v[164:165]
	v_pk_fma_f32 v[162:163], v[150:151], v[98:99], v[162:163]
	v_cndmask_b32_e64 v172, v172, v225, s[38:39]
	v_cndmask_b32_e64 v173, v173, v226, s[38:39]
	v_pk_add_f32 v[170:171], v[78:79], v[170:171]
	v_pk_add_f32 v[164:165], v[104:105], v[164:165]
	v_pk_add_f32 v[162:163], v[102:103], v[162:163]
	v_pk_mul_f32 v[172:173], v[68:69], v[172:173]
	v_cndmask_b32_e64 v176, v223, v176, s[40:41]
	v_cndmask_b32_e64 v177, v224, v177, s[40:41]
	v_pk_mul_f32 v[174:175], v[170:171], v[170:171]
	v_pk_mul_f32 v[168:169], v[164:165], v[164:165]
	v_pk_mul_f32 v[166:167], v[162:163], v[162:163]
	v_pk_fma_f32 v[172:173], v[72:73], v[176:177], v[172:173]
	v_pk_fma_f32 v[174:175], v[174:175], s[78:79], 1.0 op_sel_hi:[1,0,0]
	v_pk_fma_f32 v[168:169], v[168:169], s[78:79], 1.0 op_sel_hi:[1,0,0]
	v_pk_fma_f32 v[166:167], v[166:167], s[78:79], 1.0 op_sel_hi:[1,0,0]
	v_pk_fma_f32 v[172:173], v[148:149], v[76:77], v[172:173]
	v_pk_mul_f32 v[174:175], v[170:171], v[174:175]
	v_pk_mul_f32 v[168:169], v[164:165], v[168:169]
	v_pk_mul_f32 v[166:167], v[162:163], v[166:167]
	v_pk_add_f32 v[172:173], v[80:81], v[172:173]
	v_pk_mul_f32 v[174:175], v[174:175], s[24:25] op_sel_hi:[1,0]
	v_pk_mul_f32 v[168:169], v[168:169], s[24:25] op_sel_hi:[1,0]
	v_pk_mul_f32 v[166:167], v[166:167], s[24:25] op_sel_hi:[1,0]
	v_pk_mul_f32 v[176:177], v[172:173], v[172:173]
	v_exp_f32_e32 v174, v174
	v_exp_f32_e32 v175, v175
	v_exp_f32_e32 v168, v168
	v_exp_f32_e32 v169, v169
	v_exp_f32_e32 v166, v166
	v_exp_f32_e32 v167, v167
	v_pk_fma_f32 v[176:177], v[176:177], s[78:79], 1.0 op_sel_hi:[1,0,0]
	v_pk_add_f32 v[174:175], v[174:175], 1.0 op_sel_hi:[1,0]
	v_pk_mul_f32 v[176:177], v[172:173], v[176:177]
	v_pk_add_f32 v[168:169], v[168:169], 1.0 op_sel_hi:[1,0]
	v_pk_mul_f32 v[176:177], v[176:177], s[24:25] op_sel_hi:[1,0]
	v_pk_add_f32 v[166:167], v[166:167], 1.0 op_sel_hi:[1,0]
	v_exp_f32_e32 v176, v176
	v_exp_f32_e32 v177, v177
	v_rcp_f32_e32 v174, v174
	v_rcp_f32_e32 v175, v175
	v_rcp_f32_e32 v168, v168
	v_rcp_f32_e32 v169, v169
	v_rcp_f32_e32 v166, v166
	v_rcp_f32_e32 v167, v167
	v_pk_add_f32 v[176:177], v[176:177], 1.0 op_sel_hi:[1,0]
	v_pk_mul_f32 v[170:171], v[170:171], v[174:175]
	v_rcp_f32_e32 v176, v176
	v_rcp_f32_e32 v177, v177
	v_pk_mul_f32 v[164:165], v[164:165], v[168:169]
	v_pk_mul_f32 v[162:163], v[162:163], v[166:167]
	v_readlane_b32 s8, v253, 57
	v_pk_mul_f32 v[158:159], v[158:159], v[170:171]
	v_pk_mul_f32 v[156:157], v[156:157], v[164:165]
	v_pk_mul_f32 v[154:155], v[154:155], v[162:163]
	v_readlane_b32 s9, v253, 58
	v_cvt_pk_bf16_f32 v154, v154, v155
	v_cvt_pk_bf16_f32 v155, v156, v157
	v_cvt_pk_bf16_f32 v156, v158, v159
	s_movk_i32 s7, 0x1600
	v_pk_mul_f32 v[172:173], v[172:173], v[176:177]
	v_mov_b64_e32 v[158:159], s[8:9]
	v_mad_i64_i32 v[158:159], s[8:9], v210, s7, v[158:159]
	v_lshl_add_u64 v[158:159], v[192:193], 1, v[158:159]
	v_pk_mul_f32 v[160:161], v[160:161], v[172:173]
	s_nop 0
	v_cvt_pk_bf16_f32 v157, v160, v161
	global_store_dwordx4 v[158:159], v[154:157], off

; #define LAS __attribute__((address_space(3)))
; __device__ __forceinline__ u32x4 pack8(const float (&f)[8]) { u32x4 w; w.x = cvt_pk_bf16(f[0], f[1]); w.y = cvt_pk_bf16(f[2], f[3]); w.z = cvt_pk_bf16(f[4], f[5]); w.w = cvt_pk_bf16(f[6], f[7]); return w; }
; __device__ __forceinline__ float dpp_row_shr1(float x) { return __int_as_float(__builtin_amdgcn_update_dpp(0, __float_as_int(x), 0x111, 0xf, 0xf, false)); }
; __device__ __forceinline__ float dpp_row_shr2(float x) { return __int_as_float(__builtin_amdgcn_update_dpp(0, __float_as_int(x), 0x112, 0xf, 0xf, false)); }
;     __device__ __forceinline__ void operator()(const f32x4 (&acc)[2][2][4][2], const Unit& u, int wr, int wc, int fr, int fq) const {
;     ...
;                 if (m == 0) {
;                     if (B > 0) { const LAS float* p = XG + ((B - 1) * 2) * 128 + chl; const f32x4 r0a = *(const LAS f32x4*)p, r0b = *(const LAS f32x4*)(p + 4), r1a = *(const LAS f32x4*)(p + 128), r1b = *(const LAS f32x4*)(p + 132);
; #pragma unroll
;                         for (int j = 0; j < 4; ++j) { q14[j] = r0a[j]; q14[4 + j] = r0b[j]; q15[j] = r1a[j]; q15[4 + j] = r1b[j]; } }
;                     else {
; #pragma unroll
;                         for (int j = 0; j < 8; ++j) { q14[j] = 0.f; q15[j] = 0.f; } }
;                     float p1a[8], p2a[8];
; #pragma unroll
;                     for (int e = 0; e < 8; ++e) { const float s1 = dpp_row_shr1(g8[e]), s2 = dpp_row_shr2(g8[e]);
;                         p1a[e] = (fr >= 1) ? s1 : q15[e]; p2a[e] = (fr >= 2) ? s2 : ((fr == 1) ? q15[e] : q14[e]); }
; #pragma unroll
;                     for (int e = 0; e < 8; e += 2) { const f32x2 gt = (f32x2){w0[e], w0[e + 1]} * (f32x2){p2a[e], p2a[e + 1]} + (f32x2){w1[e], w1[e + 1]} * (f32x2){p1a[e], p1a[e + 1]} + (f32x2){w2[e], w2[e + 1]} * (f32x2){g8[e], g8[e + 1]} + (f32x2){bb[e], bb[e + 1]};
;                         const f32x2 r = gelu_tanh_mul2(gt, (f32x2){u8[e], u8[e + 1]}); o[e] = r.x; o[e + 1] = r.y; }
;     ...
;                 if (!(B == 0 && m == 0 && fr < 2)) *(u32x4*)(ACT + (size_t)(u.pm * BM + rloc) * FF + chg) = pack8(o);
.LBB0_86:
	s_nop 1
	v_mov_b32_dpp v114, v54 row_shr:1 row_mask:0xf bank_mask:0xf bound_ctrl:0
	v_mov_b32_dpp v116, v54 row_shr:2 row_mask:0xf bank_mask:0xf bound_ctrl:0
	v_mov_b32_dpp v115, v55 row_shr:1 row_mask:0xf bank_mask:0xf bound_ctrl:0
	v_mov_b32_dpp v117, v55 row_shr:2 row_mask:0xf bank_mask:0xf bound_ctrl:0
	v_mov_b32_dpp v118, v56 row_shr:1 row_mask:0xf bank_mask:0xf bound_ctrl:0
	v_mov_b32_dpp v120, v56 row_shr:2 row_mask:0xf bank_mask:0xf bound_ctrl:0
	v_mov_b32_dpp v119, v57 row_shr:1 row_mask:0xf bank_mask:0xf bound_ctrl:0
	v_mov_b32_dpp v121, v57 row_shr:2 row_mask:0xf bank_mask:0xf bound_ctrl:0
	v_mov_b32_dpp v122, v50 row_shr:1 row_mask:0xf bank_mask:0xf bound_ctrl:0
	v_mov_b32_dpp v124, v50 row_shr:2 row_mask:0xf bank_mask:0xf bound_ctrl:0
	v_mov_b32_dpp v123, v51 row_shr:1 row_mask:0xf bank_mask:0xf bound_ctrl:0
	v_mov_b32_dpp v125, v51 row_shr:2 row_mask:0xf bank_mask:0xf bound_ctrl:0
	v_mov_b32_dpp v126, v52 row_shr:1 row_mask:0xf bank_mask:0xf bound_ctrl:0
	v_mov_b32_dpp v128, v52 row_shr:2 row_mask:0xf bank_mask:0xf bound_ctrl:0
	v_mov_b32_dpp v127, v53 row_shr:1 row_mask:0xf bank_mask:0xf bound_ctrl:0
	v_mov_b32_dpp v129, v53 row_shr:2 row_mask:0xf bank_mask:0xf bound_ctrl:0
	s_and_saveexec_b64 s[30:31], s[64:65]
	s_cbranch_execz .LBB0_88
	s_waitcnt lgkmcnt(0)
	v_cndmask_b32_e64 v106, v106, v110, s[42:43]
	v_cndmask_b32_e64 v107, v107, v111, s[42:43]
	v_cndmask_b32_e64 v84, v84, v88, s[42:43]
	v_cndmask_b32_e64 v85, v85, v89, s[42:43]
	v_cndmask_b32_e64 v82, v82, v86, s[42:43]
	v_cndmask_b32_e64 v83, v83, v87, s[42:43]
	v_cndmask_b32_e64 v106, v106, v124, s[38:39]
	v_cndmask_b32_e64 v107, v107, v125, s[38:39]
	v_cndmask_b32_e64 v84, v84, v120, s[38:39]
	v_cndmask_b32_e64 v85, v85, v121, s[38:39]
	v_cndmask_b32_e64 v82, v82, v116, s[38:39]
	v_cndmask_b32_e64 v83, v83, v117, s[38:39]
	v_pk_mul_f32 v[106:107], v[66:67], v[106:107]
	v_cndmask_b32_e64 v110, v122, v110, s[40:41]
	v_cndmask_b32_e64 v111, v123, v111, s[40:41]
	v_pk_mul_f32 v[84:85], v[92:93], v[84:85]
	v_cndmask_b32_e64 v88, v118, v88, s[40:41]
	v_cndmask_b32_e64 v89, v119, v89, s[40:41]
	v_pk_mul_f32 v[82:83], v[90:91], v[82:83]
	v_cndmask_b32_e64 v86, v114, v86, s[40:41]
	v_cndmask_b32_e64 v87, v115, v87, s[40:41]
	v_pk_fma_f32 v[106:107], v[70:71], v[110:111], v[106:107]
	v_pk_fma_f32 v[84:85], v[96:97], v[88:89], v[84:85]
	v_pk_fma_f32 v[82:83], v[94:95], v[86:87], v[82:83]
	v_cndmask_b32_e64 v108, v108, v112, s[42:43]
	v_cndmask_b32_e64 v109, v109, v113, s[42:43]
	v_pk_fma_f32 v[106:107], v[50:51], v[74:75], v[106:107]
	v_pk_fma_f32 v[84:85], v[56:57], v[100:101], v[84:85]
	v_pk_fma_f32 v[82:83], v[54:55], v[98:99], v[82:83]
	v_cndmask_b32_e64 v108, v108, v128, s[38:39]
	v_cndmask_b32_e64 v109, v109, v129, s[38:39]
	v_pk_add_f32 v[106:107], v[78:79], v[106:107]
	v_pk_add_f32 v[84:85], v[104:105], v[84:85]
	v_pk_add_f32 v[82:83], v[102:103], v[82:83]
	v_pk_mul_f32 v[108:109], v[68:69], v[108:109]
	v_cndmask_b32_e64 v112, v126, v112, s[40:41]
	v_cndmask_b32_e64 v113, v127, v113, s[40:41]
	v_pk_mul_f32 v[110:111], v[106:107], v[106:107]
	v_pk_mul_f32 v[88:89], v[84:85], v[84:85]
	v_pk_mul_f32 v[86:87], v[82:83], v[82:83]
	v_pk_fma_f32 v[108:109], v[72:73], v[112:113], v[108:109]
	v_pk_fma_f32 v[110:111], v[110:111], s[78:79], 1.0 op_sel_hi:[1,0,0]
	v_pk_fma_f32 v[88:89], v[88:89], s[78:79], 1.0 op_sel_hi:[1,0,0]
	v_pk_fma_f32 v[86:87], v[86:87], s[78:79], 1.0 op_sel_hi:[1,0,0]
	v_pk_fma_f32 v[108:109], v[52:53], v[76:77], v[108:109]
	v_pk_mul_f32 v[110:111], v[106:107], v[110:111]
	v_pk_mul_f32 v[88:89], v[84:85], v[88:89]
	v_pk_mul_f32 v[86:87], v[82:83], v[86:87]
	v_pk_add_f32 v[108:109], v[80:81], v[108:109]
	v_pk_mul_f32 v[110:111], v[110:111], s[24:25] op_sel_hi:[1,0]
	v_pk_mul_f32 v[88:89], v[88:89], s[24:25] op_sel_hi:[1,0]
	v_pk_mul_f32 v[86:87], v[86:87], s[24:25] op_sel_hi:[1,0]
	v_pk_mul_f32 v[112:113], v[108:109], v[108:109]
	v_exp_f32_e32 v110, v110
	v_exp_f32_e32 v111, v111
	v_exp_f32_e32 v88, v88
	v_exp_f32_e32 v89, v89
	v_exp_f32_e32 v86, v86
	v_exp_f32_e32 v87, v87
	v_pk_fma_f32 v[112:113], v[112:113], s[78:79], 1.0 op_sel_hi:[1,0,0]
	v_pk_add_f32 v[110:111], v[110:111], 1.0 op_sel_hi:[1,0]
	v_pk_mul_f32 v[112:113], v[108:109], v[112:113]
	v_pk_add_f32 v[88:89], v[88:89], 1.0 op_sel_hi:[1,0]
	v_pk_mul_f32 v[112:113], v[112:113], s[24:25] op_sel_hi:[1,0]
	v_pk_add_f32 v[86:87], v[86:87], 1.0 op_sel_hi:[1,0]
	v_exp_f32_e32 v112, v112
	v_exp_f32_e32 v113, v113
	v_rcp_f32_e32 v110, v110
	v_rcp_f32_e32 v111, v111
	v_rcp_f32_e32 v88, v88
	v_rcp_f32_e32 v89, v89
	v_rcp_f32_e32 v86, v86
	v_rcp_f32_e32 v87, v87
	v_pk_add_f32 v[112:113], v[112:113], 1.0 op_sel_hi:[1,0]
	v_pk_mul_f32 v[106:107], v[106:107], v[110:111]
	v_rcp_f32_e32 v112, v112
	v_rcp_f32_e32 v113, v113
	v_pk_mul_f32 v[84:85], v[84:85], v[88:89]
	v_pk_mul_f32 v[82:83], v[82:83], v[86:87]
	v_readlane_b32 s8, v253, 57
	v_pk_mul_f32 v[62:63], v[62:63], v[106:107]
	v_pk_mul_f32 v[60:61], v[60:61], v[84:85]
	v_pk_mul_f32 v[58:59], v[58:59], v[82:83]
	v_readlane_b32 s9, v253, 58
	v_add_u32_e32 v122, 0x80, v210
	v_cvt_pk_bf16_f32 v58, v58, v59
	v_cvt_pk_bf16_f32 v59, v60, v61
	v_cvt_pk_bf16_f32 v60, v62, v63
	v_pk_mul_f32 v[108:109], v[108:109], v[112:113]
	v_mov_b64_e32 v[62:63], s[8:9]
	v_mad_i64_i32 v[62:63], s[8:9], v122, s10, v[62:63]
	v_lshl_add_u64 v[62:63], v[192:193], 1, v[62:63]
	v_pk_mul_f32 v[64:65], v[64:65], v[108:109]
	s_nop 0
	v_cvt_pk_bf16_f32 v61, v64, v65
	global_store_dwordx4 v[62:63], v[58:61], off
